# mla_c: all per-row loads hoisted to loop top (one memory round trip per row), counted vmcnt
# speedup vs baseline: 1.0156x; 1.0063x over previous
; __device__ __forceinline__ unsigned pk2(float lo, float hi) { f32x2_t v = {lo, hi}; bf16x2_t b = __builtin_convertvector(v, bf16x2_t); return __builtin_bit_cast(unsigned, b); }
; __device__ __forceinline__ float bflo(unsigned u) { return __uint_as_float(u << 16); }
; __device__ __forceinline__ float bfhi(unsigned u) { return __uint_as_float(u & 0xffff0000u); }
; __device__ __forceinline__ void mla_c(CArgs a, int jl, int gw, int NGW, int lane) {
;     ...
;     for (int m = gw; m < NTOK; m += NGW) {
;         const bf16_t* d = DOWN + (size_t)m * 768;
;         unsigned qv[3]; float ss = 0.f;
; #pragma unroll
;         for (int j = 0; j < 3; ++j) { qv[j] = *(const unsigned*)(d + 2 * lane + 128 * j); const float x0 = bflo(qv[j]), x1 = bfhi(qv[j]); ss += x0 * x0 + x1 * x1; }
;         const float rq = rsqrtf(wave_sum(ss) * (1.f / 384.f) + EPS);
; #pragma unroll
;         for (int j = 0; j < 3; ++j) { const int c = 2 * lane + 128 * j; *(unsigned*)(CQ + (size_t)m * 384 + c) = pk2(bflo(qv[j]) * rq * qn[c], bfhi(qv[j]) * rq * qn[c + 1]); }
;         const u32x2 kv = *(const u32x2*)(d + 384 + 4 * lane);
;         const float k0 = bflo(kv.x), k1 = bfhi(kv.x), k2 = bflo(kv.y), k3 = bfhi(kv.y);
;         const float rk = rsqrtf(wave_sum((k0 * k0 + k1 * k1) + (k2 * k2 + k3 * k3)) * (1.f / 256.f) + EPS);
;         const f32x4 g = *(const f32x4*)(kvn + 4 * lane);
;         u32x2 w; w.x = pk2(k0 * rk * g[0], k1 * rk * g[1]); w.y = pk2(k2 * rk * g[2], k3 * rk * g[3]);
;         *(u32x2*)(CKV + (size_t)m * 256 + 4 * lane) = w;
;         const float x = __uint_as_float(((unsigned)d[640 + lane]) << 16);
;         const float other = __shfl_xor(x, 32);
;         const int pos = tok_pos(m), i = lane & 31;
;         const float c = COS[pos * 32 + i], s = SIN[pos * 32 + i];
;         const float y = (lane < 32) ? (x * c - other * s) : (x * c + other * s);
;         KR[(size_t)m * 64 + lane] = (bf16_t)(pk2(y, 0.f) & 0xffffu);
;     }
.LBB0_371:
	v_lshl_add_u64 v[24:25], s[2:3], 0, v[16:17]
	v_add_co_u32_e32 v24, vcc, 0xd800000, v24
	global_load_dwordx2 v[30:31], v[4:5], off
	global_load_dwordx2 v[36:37], v[4:5], off offset:512
	v_addc_co_u32_e32 v25, vcc, 0, v25, vcc
	global_load_dword v27, v[24:25], off
	global_load_dword v29, v[24:25], off offset:256
	v_lshl_add_u64 v[32:33], s[2:3], 0, v[10:11]
	global_load_dword v25, v[24:25], off offset:512
	s_cmpk_lt_i32 s48, 0x4000
	s_movk_i32 s7, 0x7ff
	s_cselect_b32 s7, s7, 0x1fff
	s_and_b32 s7, s7, s48
	global_load_dwordx2 v[42:43], v[4:5], off offset:1024
	v_lshl_add_u64 v[46:47], s[2:3], 0, v[12:13]
	v_lshl_add_u64 v[54:55], s[2:3], 0, v[14:15]
	v_lshl_or_b32 v56, s7, 7, v0
	global_load_dwordx2 v[44:45], v[46:47], off
	global_load_dwordx4 v[48:51], v[2:3], off
	global_load_ushort v52, v[54:55], off
	global_load_dword v57, v56, s[4:5]
	global_load_dword v58, v56, s[16:17]
	s_mov_b32 s6, 0x15800000
	v_lshl_add_u64 v[10:11], v[10:11], 0, s[64:65]
	v_lshl_add_u64 v[16:17], v[16:17], 0, s[66:67]
	s_waitcnt vmcnt(8)
	v_lshlrev_b32_e32 v26, 16, v27
	v_and_b32_e32 v27, 0xffff0000, v27
	s_waitcnt vmcnt(7)
	v_lshlrev_b32_e32 v28, 16, v29
	s_waitcnt vmcnt(6)
	v_lshlrev_b32_e32 v24, 16, v25
	v_and_b32_e32 v25, 0xffff0000, v25
	v_and_b32_e32 v29, 0xffff0000, v29
	v_mov_b32_e32 v40, v27
	v_mov_b32_e32 v41, v25
	v_pk_mul_f32 v[34:35], v[28:29], v[28:29]
	v_mov_b32_e32 v38, v26
	v_mov_b32_e32 v39, v24
	v_pk_mul_f32 v[40:41], v[40:41], v[40:41]
	v_add_f32_e32 v34, v34, v35
	v_pk_fma_f32 v[38:39], v[38:39], v[38:39], v[40:41]
	s_nop 0
	v_add_f32_e32 v34, v38, v34
	v_add_f32_e32 v34, v34, v39
	ds_bpermute_b32 v35, v18, v34
	s_waitcnt lgkmcnt(0)
	v_add_f32_e32 v34, v34, v35
	ds_bpermute_b32 v35, v19, v34
	s_waitcnt lgkmcnt(0)
	v_add_f32_e32 v34, v34, v35
	ds_bpermute_b32 v35, v20, v34
	s_waitcnt lgkmcnt(0)
	v_add_f32_e32 v34, v34, v35
	ds_bpermute_b32 v35, v21, v34
	s_waitcnt lgkmcnt(0)
	v_add_f32_e32 v34, v34, v35
	ds_bpermute_b32 v35, v22, v34
	s_waitcnt lgkmcnt(0)
	v_add_f32_e32 v34, v34, v35
	ds_bpermute_b32 v35, v23, v34
	s_waitcnt lgkmcnt(0)
	v_add_f32_e32 v34, v34, v35
	v_fmamk_f32 v34, v34, 0x3b2aaaab, v201
	v_cmp_gt_f32_e32 vcc, s55, v34
	v_mul_f32_e32 v35, 0x4b800000, v34
	s_nop 0
	v_cndmask_b32_e32 v34, v34, v35, vcc
	v_rsq_f32_e32 v34, v34
	s_nop 0
	v_mul_f32_e32 v35, 0x45800000, v34
	v_cndmask_b32_e32 v34, v34, v35, vcc
	v_pk_mul_f32 v[26:27], v[34:35], v[26:27] op_sel_hi:[0,1]
	v_pk_mul_f32 v[26:27], v[30:31], v[26:27]
	v_pk_mul_f32 v[28:29], v[34:35], v[28:29] op_sel_hi:[0,1]
	v_cvt_pk_bf16_f32 v30, v26, v27
	v_add_co_u32_e32 v26, vcc, s6, v32
	v_pk_mul_f32 v[28:29], v[36:37], v[28:29]
	s_nop 0
	v_addc_co_u32_e32 v27, vcc, 0, v33, vcc
	v_cvt_pk_bf16_f32 v28, v28, v29
	global_store_dword v[26:27], v28, off offset:256
	v_pk_mul_f32 v[24:25], v[34:35], v[24:25] op_sel_hi:[0,1]
	global_store_dword v[26:27], v30, off
	s_add_i32 s48, s48, s54
	s_cmpk_gt_i32 s48, 0x7fff
	s_waitcnt vmcnt(7)
	v_pk_mul_f32 v[24:25], v[42:43], v[24:25]
	s_nop 0
	v_cvt_pk_bf16_f32 v24, v24, v25
	global_store_dword v[26:27], v24, off offset:512
	v_lshl_add_u64 v[12:13], v[12:13], 0, s[66:67]
	s_waitcnt vmcnt(7)
	v_and_b32_e32 v31, 0xffff0000, v45
	v_and_b32_e32 v33, 0xffff0000, v44
	v_lshlrev_b32_e32 v30, 16, v45
	v_lshlrev_b32_e32 v32, 16, v44
	v_mov_b32_e32 v34, v33
	v_mov_b32_e32 v35, v31
	v_mov_b32_e32 v28, v32
	v_mov_b32_e32 v29, v30
	v_pk_mul_f32 v[34:35], v[34:35], v[34:35]
	s_nop 0
	v_pk_fma_f32 v[28:29], v[28:29], v[28:29], v[34:35]
	s_nop 0
	v_add_f32_e32 v28, v28, v29
	ds_bpermute_b32 v29, v18, v28
	s_waitcnt lgkmcnt(0)
	v_add_f32_e32 v28, v28, v29
	ds_bpermute_b32 v29, v19, v28
	s_waitcnt lgkmcnt(0)
	v_add_f32_e32 v28, v28, v29
	ds_bpermute_b32 v29, v20, v28
	s_waitcnt lgkmcnt(0)
	v_add_f32_e32 v28, v28, v29
	ds_bpermute_b32 v29, v21, v28
	s_waitcnt lgkmcnt(0)
	v_add_f32_e32 v28, v28, v29
	ds_bpermute_b32 v29, v22, v28
	s_waitcnt lgkmcnt(0)
	v_add_f32_e32 v28, v28, v29
	ds_bpermute_b32 v29, v23, v28
	s_waitcnt lgkmcnt(0)
	v_add_f32_e32 v28, v28, v29
	v_fmamk_f32 v28, v28, 0x3b800000, v201
	v_cmp_gt_f32_e32 vcc, s55, v28
	v_mul_f32_e32 v29, 0x4b800000, v28
	s_nop 0
	v_cndmask_b32_e32 v28, v28, v29, vcc
	v_rsq_f32_e32 v28, v28
	s_nop 0
	v_mul_f32_e32 v29, 0x45800000, v28
	v_cndmask_b32_e32 v28, v28, v29, vcc
	v_pk_mul_f32 v[32:33], v[28:29], v[32:33] op_sel_hi:[0,1]
	v_pk_mul_f32 v[28:29], v[28:29], v[30:31] op_sel_hi:[0,1]
	s_waitcnt vmcnt(6)
	v_pk_mul_f32 v[24:25], v[48:49], v[32:33]
	v_pk_mul_f32 v[26:27], v[50:51], v[28:29]
	v_cvt_pk_bf16_f32 v24, v24, v25
	v_cvt_pk_bf16_f32 v25, v26, v27
	v_lshl_add_u64 v[26:27], s[2:3], 0, v[8:9]
	global_store_dwordx2 v[26:27], v[24:25], off
	v_lshl_add_u64 v[8:9], v[8:9], 0, s[72:73]
	v_lshl_add_u64 v[14:15], v[14:15], 0, s[66:67]
	s_waitcnt vmcnt(6)
	v_lshlrev_b32_e32 v24, 16, v52
	ds_bpermute_b32 v25, v23, v24
	s_waitcnt vmcnt(4) lgkmcnt(0)
	v_mul_f32_e32 v25, v58, v25
	v_cndmask_b32_e64 v25, v25, -v25, s[38:39]
	v_fmac_f32_e32 v25, v57, v24
	v_cvt_pk_bf16_f32 v26, v25, s0
	v_lshl_add_u64 v[24:25], s[2:3], 0, v[6:7]
	v_lshl_add_u64 v[6:7], v[6:7], 0, s[68:69]
	global_store_short v[24:25], v26, off
	s_cbranch_scc0 .LBB0_371
